# v161 plus s_setprio 1 around the GQA QK MFMA cluster (0 from softmax on)
# baseline (speedup 1.0000x reference)
; #define MFMA(a, b, c) __builtin_amdgcn_mfma_f32_32x32x16_bf16((a), (b), (c), 0, 0, 0)
; DI float fexp2(float x) { return __builtin_amdgcn_exp2f(x); }
; DI void flash_pass_q2(f32x16 (&o)[2][2], const u16* __restrict__ Qp0, const u16* __restrict__ Qp1,
;                       const u16* __restrict__ Kb, int ldk, const u16* __restrict__ Vt, int S, int ntiles, char* lds) {
;     ...
;     {
;       bf16x8 ka[4], kb_[4];
; #pragma unroll
;       for (int ks = 0; ks < 4; ++ks) {
;         const int co = ((2 * ks + h) ^ ksw) << 4;
;         ka[ks] = *(const bf16x8*)(st + pr * 128 + co);
;         kb_[ks] = *(const bf16x8*)(st + (32 + pr) * 128 + co);
;       }
;       asm volatile("" ::: "memory");
; #pragma unroll
;       for (int ks = 0; ks < 4; ++ks) {
;         s[0][0] = MFMA(ka[ks], q[0][ks], s[0][0]);
;         s[0][1] = MFMA(kb_[ks], q[0][ks], s[0][1]);
;         s[1][0] = MFMA(ka[ks], q[1][ks], s[1][0]);
;         s[1][1] = MFMA(kb_[ks], q[1][ks], s[1][1]);
;       }
;     }
;     bf16x8 pf[2][2][2];
; #pragma unroll
;     for (int hq = 0; hq < 2; ++hq) {
;       float t[32];
; #pragma unroll
;       for (int i = 0; i < 16; ++i) { t[i] = s[hq][0][i]; t[16 + i] = s[hq][1][i]; }
;       float mx = t[0];
; #pragma unroll
;       for (int e = 1; e < 32; ++e) mx = fmaxf(mx, t[e]);
;       mx = fmaxf(mx, __shfl_xor(mx, 32));
;       if (__builtin_amdgcn_ballot_w64(mx > m_run[hq] + 8.f) != 0ull) {
;         const float m_new = fmaxf(m_run[hq], mx);
;         const float alpha = fexp2(m_run[hq] - m_new);
;         l_run[hq] *= alpha;
;         m_run[hq] = m_new;
; #pragma unroll
;         for (int mv = 0; mv < 2; ++mv)
; #pragma unroll
;           for (int i = 0; i < 16; ++i) o[hq][mv][i] *= alpha;
;       }
;       float ls = 0.f;
; #pragma unroll
;       for (int e = 0; e < 32; ++e) { t[e] = fexp2(t[e] - m_run[hq]); ls += t[e]; }
.Lg2_dmadonef:
	s_setprio 1
	v_cmp_eq_u32_e32 vcc, s22, v185
	s_waitcnt lgkmcnt(2)
	v_mfma_f32_32x32x16_bf16 v[128:143], v[2:5], v[168:171], 0
	v_mfma_f32_32x32x16_bf16 v[112:127], v[6:9], v[168:171], 0
	v_mfma_f32_32x32x16_bf16 v[96:111], v[2:5], v[172:175], 0
	v_mfma_f32_32x32x16_bf16 v[80:95], v[6:9], v[172:175], 0
	s_or_b64 s[18:19], vcc, s[18:19]
	v_add_u32_e32 v249, v11, v235
	ds_read_b128 v[2:5], v249
	ds_read_b128 v[6:9], v249 offset:4096
	s_waitcnt lgkmcnt(2)
	v_mfma_f32_32x32x16_bf16 v[128:143], v[12:15], v[164:167], v[128:143]
	v_mfma_f32_32x32x16_bf16 v[112:127], v[240:243], v[164:167], v[112:127]
	v_mfma_f32_32x32x16_bf16 v[96:111], v[12:15], v[160:163], v[96:111]
	v_mfma_f32_32x32x16_bf16 v[80:95], v[240:243], v[160:163], v[80:95]
	v_add_u32_e32 v249, v11, v234
	ds_read_b128 v[12:15], v249
	ds_read_b128 v[240:243], v249 offset:4096
	s_waitcnt lgkmcnt(2)
	v_mfma_f32_32x32x16_bf16 v[128:143], v[2:5], v[156:159], v[128:143]
	v_mfma_f32_32x32x16_bf16 v[112:127], v[6:9], v[156:159], v[112:127]
	v_mfma_f32_32x32x16_bf16 v[96:111], v[2:5], v[152:155], v[96:111]
	v_mfma_f32_32x32x16_bf16 v[80:95], v[6:9], v[152:155], v[80:95]
	v_add_u32_e32 v249, v248, v232
	ds_read_b128 v[2:5], v249 offset:8192
	ds_read_b128 v[6:9], v249 offset:12288
	s_waitcnt lgkmcnt(2)
	v_mfma_f32_32x32x16_bf16 v[128:143], v[12:15], v[148:151], v[128:143]
	v_mfma_f32_32x32x16_bf16 v[112:127], v[240:243], v[148:151], v[112:127]
	v_mfma_f32_32x32x16_bf16 v[96:111], v[12:15], v[144:147], v[96:111]
	v_mfma_f32_32x32x16_bf16 v[80:95], v[240:243], v[144:147], v[80:95]
	v_add_u32_e32 v249, v248, v231
	ds_read_b128 v[12:15], v249 offset:8192
	ds_read_b128 v[240:243], v249 offset:12288
	s_nop 5
	v_exp_f32_e32 v128, v128
	s_setprio 0
	v_exp_f32_e32 v129, v129
	v_exp_f32_e32 v130, v130
	v_exp_f32_e32 v131, v131
	v_exp_f32_e32 v132, v132
	v_exp_f32_e32 v133, v133
	v_exp_f32_e32 v134, v134
	v_exp_f32_e32 v135, v135
	v_exp_f32_e32 v136, v136
	v_exp_f32_e32 v137, v137
	v_add_f32_e32 v210, v128, v130
	v_add_f32_e32 v246, v129, v131
	v_exp_f32_e32 v138, v138
	v_exp_f32_e32 v139, v139
	v_add_f32_e32 v210, v210, v132
	v_add_f32_e32 v246, v246, v133
	v_exp_f32_e32 v140, v140
	v_exp_f32_e32 v141, v141
	v_add_f32_e32 v210, v210, v134
	v_add_f32_e32 v246, v246, v135
	v_exp_f32_e32 v142, v142
	v_exp_f32_e32 v143, v143
	v_add_f32_e32 v210, v210, v136
	v_add_f32_e32 v246, v246, v137
	v_exp_f32_e32 v112, v112
	v_exp_f32_e32 v113, v113
	v_add_f32_e32 v210, v210, v138
	v_add_f32_e32 v246, v246, v139
	v_exp_f32_e32 v114, v114
	v_exp_f32_e32 v115, v115
	v_add_f32_e32 v210, v210, v140
	v_add_f32_e32 v246, v246, v141
	v_exp_f32_e32 v116, v116
	v_exp_f32_e32 v117, v117
	v_add_f32_e32 v210, v210, v142
	v_add_f32_e32 v246, v246, v143
	v_exp_f32_e32 v118, v118
	v_exp_f32_e32 v119, v119
	v_add_f32_e32 v210, v210, v112
	v_add_f32_e32 v246, v246, v113
	v_exp_f32_e32 v120, v120
	v_exp_f32_e32 v121, v121
	v_add_f32_e32 v210, v210, v114
	v_add_f32_e32 v246, v246, v115
	v_exp_f32_e32 v122, v122
	v_exp_f32_e32 v123, v123
	v_add_f32_e32 v210, v210, v116
	v_add_f32_e32 v246, v246, v117
	v_exp_f32_e32 v124, v124
	v_exp_f32_e32 v125, v125
	v_add_f32_e32 v210, v210, v118
	v_add_f32_e32 v246, v246, v119
	v_exp_f32_e32 v126, v126
	v_exp_f32_e32 v127, v127
	v_add_f32_e32 v210, v210, v120
	v_add_f32_e32 v246, v246, v121
	v_add_f32_e32 v210, v210, v122
	v_add_f32_e32 v246, v246, v123
	v_add_f32_e32 v210, v210, v124
	v_add_f32_e32 v246, v246, v125
	v_add_f32_e32 v210, v210, v126
	v_add_f32_e32 v246, v246, v127
	v_add_f32_e32 v210, v210, v246
	v_cmp_lt_f32_e32 vcc, 0x5d800000, v210
	s_cbranch_vccnz .Lg3_ovf0
	v_cmp_gt_f32_e32 vcc, s100, v210
	s_cbranch_vccnz .Lg3_unf0
; #define MFMA(a, b, c) __builtin_amdgcn_mfma_f32_32x32x16_bf16((a), (b), (c), 0, 0, 0)
; DI float fexp2(float x) { return __builtin_amdgcn_exp2f(x); }
; DI void flash_pass_q2(f32x16 (&o)[2][2], const u16* __restrict__ Qp0, const u16* __restrict__ Qp1,
;                       const u16* __restrict__ Kb, int ldk, const u16* __restrict__ Vt, int S, int ntiles, char* lds) {
;     ...
;       float ls = 0.f;
; #pragma unroll
;       for (int e = 0; e < 32; ++e) { t[e] = fexp2(t[e] - m_run[hq]); ls += t[e]; }
;       l_run[hq] += ls;
; #pragma unroll
;       for (int kb = 0; kb < 2; ++kb)
; #pragma unroll
;         for (int c2 = 0; c2 < 2; ++c2) {
;           const int e0 = kb * 16 + c2 * 8;
;           u32x4 pw = {pk_bf16(t[e0], t[e0 + 1]), pk_bf16(t[e0 + 2], t[e0 + 3]), pk_bf16(t[e0 + 4], t[e0 + 5]), pk_bf16(t[e0 + 6], t[e0 + 7])};
;           pf[hq][kb][c2] = __builtin_bit_cast(bf16x8, pw);
;         }
;     }
;     bf16x8 vf[2][2][2];
; #pragma unroll
;     for (int kb = 0; kb < 2; ++kb)
; #pragma unroll
;       for (int c2 = 0; c2 < 2; ++c2) {
;         const int co = ((4 * kb + 2 * c2 + h) ^ vsw) << 4;
; #pragma unroll
;         for (int mv = 0; mv < 2; ++mv) vf[kb][c2][mv] = *(const bf16x8*)(st + 8192 + (mv * 32 + r) * 128 + co);
;       }
;     asm volatile("" ::: "memory");
; #pragma unroll
;     for (int kb = 0; kb < 2; ++kb)
; #pragma unroll
;       for (int c2 = 0; c2 < 2; ++c2)
; #pragma unroll
;         for (int mv = 0; mv < 2; ++mv) {
;           o[0][mv] = MFMA(vf[kb][c2][mv], pf[0][kb][c2], o[0][mv]);
;           o[1][mv] = MFMA(vf[kb][c2][mv], pf[1][kb][c2], o[1][mv]);
;         }
;     __syncthreads();
	v_add_f32_e32 v0, v0, v210
	v_cvt_pk_bf16_f32 v128, v128, v129
	v_cvt_pk_bf16_f32 v129, v130, v131
	v_cvt_pk_bf16_f32 v130, v132, v133
	v_cvt_pk_bf16_f32 v131, v134, v135
	v_cvt_pk_bf16_f32 v136, v136, v137
	v_cvt_pk_bf16_f32 v137, v138, v139
	v_cvt_pk_bf16_f32 v138, v140, v141
	v_cvt_pk_bf16_f32 v139, v142, v143
	v_cvt_pk_bf16_f32 v112, v112, v113
	v_cvt_pk_bf16_f32 v113, v114, v115
	v_cvt_pk_bf16_f32 v114, v116, v117
	v_cvt_pk_bf16_f32 v115, v118, v119
	v_cvt_pk_bf16_f32 v120, v120, v121
	v_cvt_pk_bf16_f32 v121, v122, v123
	v_cvt_pk_bf16_f32 v122, v124, v125
	v_cvt_pk_bf16_f32 v123, v126, v127
	s_waitcnt lgkmcnt(0)
	v_mfma_f32_32x32x16_bf16 v[64:79], v[2:5], v[128:131], v[64:79]
	v_mfma_f32_32x32x16_bf16 v[48:63], v[6:9], v[128:131], v[48:63]
	v_mfma_f32_32x32x16_bf16 v[64:79], v[12:15], v[136:139], v[64:79]
	v_mfma_f32_32x32x16_bf16 v[48:63], v[240:243], v[136:139], v[48:63]
	v_exp_f32_e32 v96, v96
	v_exp_f32_e32 v97, v97
	v_exp_f32_e32 v98, v98
	v_exp_f32_e32 v99, v99
	v_exp_f32_e32 v100, v100
	v_exp_f32_e32 v101, v101
	v_exp_f32_e32 v102, v102
	v_exp_f32_e32 v103, v103
	v_exp_f32_e32 v104, v104
	v_exp_f32_e32 v105, v105
	v_add_f32_e32 v210, v96, v98
	v_add_f32_e32 v246, v97, v99
	v_exp_f32_e32 v106, v106
	v_exp_f32_e32 v107, v107
	v_add_f32_e32 v210, v210, v100
	v_add_f32_e32 v246, v246, v101
	v_exp_f32_e32 v108, v108
	v_exp_f32_e32 v109, v109
	v_add_f32_e32 v210, v210, v102
	v_add_f32_e32 v246, v246, v103
	v_exp_f32_e32 v110, v110
	v_exp_f32_e32 v111, v111
	v_add_f32_e32 v210, v210, v104
	v_add_f32_e32 v246, v246, v105
	v_exp_f32_e32 v80, v80
	v_exp_f32_e32 v81, v81
	v_add_f32_e32 v210, v210, v106
	v_add_f32_e32 v246, v246, v107
	v_exp_f32_e32 v82, v82
	v_exp_f32_e32 v83, v83
	v_add_f32_e32 v210, v210, v108
	v_add_f32_e32 v246, v246, v109
	v_exp_f32_e32 v84, v84
	v_exp_f32_e32 v85, v85
	v_add_f32_e32 v210, v210, v110
	v_add_f32_e32 v246, v246, v111
	v_exp_f32_e32 v86, v86
	v_exp_f32_e32 v87, v87
	v_add_f32_e32 v210, v210, v80
	v_add_f32_e32 v246, v246, v81
	v_exp_f32_e32 v88, v88
	v_exp_f32_e32 v89, v89
	v_add_f32_e32 v210, v210, v82
	v_add_f32_e32 v246, v246, v83
	v_exp_f32_e32 v90, v90
	v_exp_f32_e32 v91, v91
	v_add_f32_e32 v210, v210, v84
	v_add_f32_e32 v246, v246, v85
	v_exp_f32_e32 v92, v92
	v_exp_f32_e32 v93, v93
	v_add_f32_e32 v210, v210, v86
	v_add_f32_e32 v246, v246, v87
	v_exp_f32_e32 v94, v94
	v_exp_f32_e32 v95, v95
	v_add_f32_e32 v210, v210, v88
	v_add_f32_e32 v246, v246, v89
	v_add_f32_e32 v210, v210, v90
	v_add_f32_e32 v246, v246, v91
	v_add_f32_e32 v210, v210, v92
	v_add_f32_e32 v246, v246, v93
	v_add_f32_e32 v210, v210, v94
	v_add_f32_e32 v246, v246, v95
	v_add_f32_e32 v210, v210, v246
	v_cmp_lt_f32_e32 vcc, 0x5d800000, v210
	s_cbranch_vccnz .Lg3_ovf1
	v_cmp_gt_f32_e32 vcc, s100, v210
	s_cbranch_vccnz .Lg3_unf1
	v_add_f32_e32 v229, v229, v210
	v_cvt_pk_bf16_f32 v96, v96, v97
	v_cvt_pk_bf16_f32 v97, v98, v99
	v_cvt_pk_bf16_f32 v98, v100, v101
	v_cvt_pk_bf16_f32 v99, v102, v103
	v_cvt_pk_bf16_f32 v104, v104, v105
	v_cvt_pk_bf16_f32 v105, v106, v107
	v_cvt_pk_bf16_f32 v106, v108, v109
	v_cvt_pk_bf16_f32 v107, v110, v111
	v_cvt_pk_bf16_f32 v80, v80, v81
	v_cvt_pk_bf16_f32 v81, v82, v83
	v_cvt_pk_bf16_f32 v82, v84, v85
	v_cvt_pk_bf16_f32 v83, v86, v87
	v_cvt_pk_bf16_f32 v88, v88, v89
	v_cvt_pk_bf16_f32 v89, v90, v91
	v_cvt_pk_bf16_f32 v90, v92, v93
	v_cvt_pk_bf16_f32 v91, v94, v95
	v_mfma_f32_32x32x16_bf16 v[32:47], v[2:5], v[96:99], v[32:47]
	v_mfma_f32_32x32x16_bf16 v[16:31], v[6:9], v[96:99], v[16:31]
	v_add_u32_e32 v249, v248, v230
	ds_read_b128 v[2:5], v249 offset:8192
	ds_read_b128 v[6:9], v249 offset:12288
	v_mfma_f32_32x32x16_bf16 v[32:47], v[12:15], v[104:107], v[32:47]
	v_mfma_f32_32x32x16_bf16 v[16:31], v[240:243], v[104:107], v[16:31]
	v_add_u32_e32 v249, v248, v228
	ds_read_b128 v[12:15], v249 offset:8192
	ds_read_b128 v[240:243], v249 offset:12288
	s_waitcnt lgkmcnt(2)
	v_mfma_f32_32x32x16_bf16 v[64:79], v[2:5], v[112:115], v[64:79]
	v_mfma_f32_32x32x16_bf16 v[48:63], v[6:9], v[112:115], v[48:63]
	v_mfma_f32_32x32x16_bf16 v[32:47], v[2:5], v[80:83], v[32:47]
	v_mfma_f32_32x32x16_bf16 v[16:31], v[6:9], v[80:83], v[16:31]
	s_waitcnt lgkmcnt(0)
	v_mfma_f32_32x32x16_bf16 v[64:79], v[12:15], v[120:123], v[64:79]
	v_mfma_f32_32x32x16_bf16 v[48:63], v[240:243], v[120:123], v[48:63]
	v_mfma_f32_32x32x16_bf16 v[32:47], v[12:15], v[88:91], v[32:47]
	v_mfma_f32_32x32x16_bf16 v[16:31], v[240:243], v[88:91], v[16:31]
	s_add_u32 s29, s21, s23
	s_mov_b32 s23, s21
	s_sub_u32 s21, 0x12000, s29
	v_mov_b32_e32 v14, s21
	s_waitcnt vmcnt(2)
	s_waitcnt lgkmcnt(0)
	s_barrier
	s_andn2_b64 exec, exec, s[18:19]
	s_mov_b32 s100, 0
	s_cbranch_execnz .LBB0_280
	v_readfirstlane_b32 s101, v204
	s_nop 0
	s_lshr_b32 s101, s101, 8
	s_branch .LBB0_286

; #define MFMA(a, b, c) __builtin_amdgcn_mfma_f32_32x32x16_bf16((a), (b), (c), 0, 0, 0)
; DI float fexp2(float x) { return __builtin_amdgcn_exp2f(x); }
; DI void flash_pass_q2(f32x16 (&o)[2][2], const u16* __restrict__ Qp0, const u16* __restrict__ Qp1,
;                       const u16* __restrict__ Kb, int ldk, const u16* __restrict__ Vt, int S, int ntiles, char* lds) {
;     ...
;     {
;       bf16x8 ka[4], kb_[4];
; #pragma unroll
;       for (int ks = 0; ks < 4; ++ks) {
;         const int co = ((2 * ks + h) ^ ksw) << 4;
;         ka[ks] = *(const bf16x8*)(st + pr * 128 + co);
;         kb_[ks] = *(const bf16x8*)(st + (32 + pr) * 128 + co);
;       }
;       asm volatile("" ::: "memory");
; #pragma unroll
;       for (int ks = 0; ks < 4; ++ks) {
;         s[0][0] = MFMA(ka[ks], q[0][ks], s[0][0]);
;         s[0][1] = MFMA(kb_[ks], q[0][ks], s[0][1]);
;         s[1][0] = MFMA(ka[ks], q[1][ks], s[1][0]);
;         s[1][1] = MFMA(kb_[ks], q[1][ks], s[1][1]);
;       }
;     }
;     bf16x8 pf[2][2][2];
; #pragma unroll
;     for (int hq = 0; hq < 2; ++hq) {
;       float t[32];
; #pragma unroll
;       for (int i = 0; i < 16; ++i) { t[i] = s[hq][0][i]; t[16 + i] = s[hq][1][i]; }
;       float mx = t[0];
; #pragma unroll
;       for (int e = 1; e < 32; ++e) mx = fmaxf(mx, t[e]);
;       mx = fmaxf(mx, __shfl_xor(mx, 32));
;       if (__builtin_amdgcn_ballot_w64(mx > m_run[hq] + 8.f) != 0ull) {
;         const float m_new = fmaxf(m_run[hq], mx);
;         const float alpha = fexp2(m_run[hq] - m_new);
;         l_run[hq] *= alpha;
;         m_run[hq] = m_new;
; #pragma unroll
;         for (int mv = 0; mv < 2; ++mv)
; #pragma unroll
;           for (int i = 0; i < 16; ++i) o[hq][mv][i] *= alpha;
;       }
;       float ls = 0.f;
; #pragma unroll
;       for (int e = 0; e < 32; ++e) { t[e] = fexp2(t[e] - m_run[hq]); ls += t[e]; }
;       l_run[hq] += ls;
; #pragma unroll
;       for (int kb = 0; kb < 2; ++kb)
; #pragma unroll
;         for (int c2 = 0; c2 < 2; ++c2) {
;           const int e0 = kb * 16 + c2 * 8;
;           u32x4 pw = {pk_bf16(t[e0], t[e0 + 1]), pk_bf16(t[e0 + 2], t[e0 + 3]), pk_bf16(t[e0 + 4], t[e0 + 5]), pk_bf16(t[e0 + 6], t[e0 + 7])};
;           pf[hq][kb][c2] = __builtin_bit_cast(bf16x8, pw);
;         }
.Lg2_dmadone:
	s_setprio 1
	v_cmp_eq_u32_e32 vcc, s22, v185
	s_waitcnt lgkmcnt(2)
	v_mfma_f32_32x32x16_bf16 v[128:143], v[2:5], v[168:171], 0
	v_mfma_f32_32x32x16_bf16 v[112:127], v[6:9], v[168:171], 0
	v_mfma_f32_32x32x16_bf16 v[96:111], v[2:5], v[172:175], 0
	v_mfma_f32_32x32x16_bf16 v[80:95], v[6:9], v[172:175], 0
	s_or_b64 s[18:19], vcc, s[18:19]
	v_add_u32_e32 v249, v11, v235
	ds_read_b128 v[2:5], v249
	ds_read_b128 v[6:9], v249 offset:4096
	s_waitcnt lgkmcnt(2)
	v_mfma_f32_32x32x16_bf16 v[128:143], v[12:15], v[164:167], v[128:143]
	v_mfma_f32_32x32x16_bf16 v[112:127], v[240:243], v[164:167], v[112:127]
	v_mfma_f32_32x32x16_bf16 v[96:111], v[12:15], v[160:163], v[96:111]
	v_mfma_f32_32x32x16_bf16 v[80:95], v[240:243], v[160:163], v[80:95]
	v_add_u32_e32 v249, v11, v234
	ds_read_b128 v[12:15], v249
	ds_read_b128 v[240:243], v249 offset:4096
	s_waitcnt lgkmcnt(2)
	v_mfma_f32_32x32x16_bf16 v[128:143], v[2:5], v[156:159], v[128:143]
	v_mfma_f32_32x32x16_bf16 v[112:127], v[6:9], v[156:159], v[112:127]
	v_mfma_f32_32x32x16_bf16 v[96:111], v[2:5], v[152:155], v[96:111]
	v_mfma_f32_32x32x16_bf16 v[80:95], v[6:9], v[152:155], v[80:95]
	v_add_u32_e32 v249, v248, v232
	ds_read_b128 v[2:5], v249 offset:8192
	ds_read_b128 v[6:9], v249 offset:12288
	s_waitcnt lgkmcnt(2)
	v_mfma_f32_32x32x16_bf16 v[128:143], v[12:15], v[148:151], v[128:143]
	v_mfma_f32_32x32x16_bf16 v[112:127], v[240:243], v[148:151], v[112:127]
	v_mfma_f32_32x32x16_bf16 v[96:111], v[12:15], v[144:147], v[96:111]
	v_mfma_f32_32x32x16_bf16 v[80:95], v[240:243], v[144:147], v[80:95]
	v_add_u32_e32 v249, v248, v231
	ds_read_b128 v[12:15], v249 offset:8192
	ds_read_b128 v[240:243], v249 offset:12288
.Lg2_sm0:
	s_setprio 0
	s_nop 5
	v_sub_f32_e32 v128, v128, v10
	v_sub_f32_e32 v129, v129, v10
	v_sub_f32_e32 v130, v130, v10
	v_sub_f32_e32 v131, v131, v10
	v_sub_f32_e32 v132, v132, v10
	v_sub_f32_e32 v133, v133, v10
	v_sub_f32_e32 v134, v134, v10
	v_sub_f32_e32 v135, v135, v10
	v_sub_f32_e32 v136, v136, v10
	v_sub_f32_e32 v137, v137, v10
	v_sub_f32_e32 v138, v138, v10
	v_sub_f32_e32 v139, v139, v10
	v_sub_f32_e32 v140, v140, v10
	v_sub_f32_e32 v141, v141, v10
	v_sub_f32_e32 v142, v142, v10
	v_sub_f32_e32 v143, v143, v10
	v_sub_f32_e32 v112, v112, v10
	v_sub_f32_e32 v113, v113, v10
	v_sub_f32_e32 v114, v114, v10
	v_sub_f32_e32 v115, v115, v10
	v_sub_f32_e32 v116, v116, v10
	v_sub_f32_e32 v117, v117, v10
	v_sub_f32_e32 v118, v118, v10
	v_sub_f32_e32 v119, v119, v10
	v_sub_f32_e32 v120, v120, v10
	v_sub_f32_e32 v121, v121, v10
	v_sub_f32_e32 v122, v122, v10
	v_sub_f32_e32 v123, v123, v10
	v_sub_f32_e32 v124, v124, v10
	v_sub_f32_e32 v125, v125, v10
	v_sub_f32_e32 v126, v126, v10
	v_sub_f32_e32 v127, v127, v10
	v_exp_f32_e32 v128, v128
	v_exp_f32_e32 v129, v129
	v_exp_f32_e32 v130, v130
	v_exp_f32_e32 v131, v131
	v_exp_f32_e32 v132, v132
	v_exp_f32_e32 v133, v133
	v_exp_f32_e32 v134, v134
	v_exp_f32_e32 v135, v135
	v_exp_f32_e32 v136, v136
	v_exp_f32_e32 v137, v137
	v_add_f32_e32 v210, v128, v130
	v_add_f32_e32 v246, v129, v131
	v_exp_f32_e32 v138, v138
	v_exp_f32_e32 v139, v139
	v_add_f32_e32 v210, v210, v132
	v_add_f32_e32 v246, v246, v133
	v_exp_f32_e32 v140, v140
	v_exp_f32_e32 v141, v141
	v_add_f32_e32 v210, v210, v134
	v_add_f32_e32 v246, v246, v135
	v_exp_f32_e32 v142, v142
	v_exp_f32_e32 v143, v143
	v_add_f32_e32 v210, v210, v136
	v_add_f32_e32 v246, v246, v137
	v_exp_f32_e32 v112, v112
	v_exp_f32_e32 v113, v113
	v_add_f32_e32 v210, v210, v138
	v_add_f32_e32 v246, v246, v139
	v_exp_f32_e32 v114, v114
	v_exp_f32_e32 v115, v115
	v_add_f32_e32 v210, v210, v140
	v_add_f32_e32 v246, v246, v141
	v_exp_f32_e32 v116, v116
	v_exp_f32_e32 v117, v117
	v_add_f32_e32 v210, v210, v142
	v_add_f32_e32 v246, v246, v143
	v_exp_f32_e32 v118, v118
	v_exp_f32_e32 v119, v119
	v_add_f32_e32 v210, v210, v112
	v_add_f32_e32 v246, v246, v113
	v_exp_f32_e32 v120, v120
	v_exp_f32_e32 v121, v121
	v_add_f32_e32 v210, v210, v114
	v_add_f32_e32 v246, v246, v115
	v_exp_f32_e32 v122, v122
	v_exp_f32_e32 v123, v123
	v_add_f32_e32 v210, v210, v116
	v_add_f32_e32 v246, v246, v117
	v_exp_f32_e32 v124, v124
	v_exp_f32_e32 v125, v125
	v_add_f32_e32 v210, v210, v118
	v_add_f32_e32 v246, v246, v119
	v_exp_f32_e32 v126, v126
	v_exp_f32_e32 v127, v127
	v_add_f32_e32 v210, v210, v120
	v_add_f32_e32 v246, v246, v121
	v_add_f32_e32 v210, v210, v122
	v_add_f32_e32 v246, v246, v123
	v_add_f32_e32 v210, v210, v124
	v_add_f32_e32 v246, v246, v125
	v_add_f32_e32 v210, v210, v126
	v_add_f32_e32 v246, v246, v127
	v_add_f32_e32 v210, v210, v246
	v_cmp_lt_f32_e32 vcc, 0x5d800000, v210
	s_cbranch_vccnz .Lg2_fix0
	v_add_f32_e32 v0, v0, v210
	v_cvt_pk_bf16_f32 v128, v128, v129
	v_cvt_pk_bf16_f32 v129, v130, v131
	v_cvt_pk_bf16_f32 v130, v132, v133
	v_cvt_pk_bf16_f32 v131, v134, v135
	v_cvt_pk_bf16_f32 v136, v136, v137
	v_cvt_pk_bf16_f32 v137, v138, v139
	v_cvt_pk_bf16_f32 v138, v140, v141
	v_cvt_pk_bf16_f32 v139, v142, v143
	v_cvt_pk_bf16_f32 v112, v112, v113
	v_cvt_pk_bf16_f32 v113, v114, v115
	v_cvt_pk_bf16_f32 v114, v116, v117
	v_cvt_pk_bf16_f32 v115, v118, v119
	v_cvt_pk_bf16_f32 v120, v120, v121
	v_cvt_pk_bf16_f32 v121, v122, v123
	v_cvt_pk_bf16_f32 v122, v124, v125
	v_cvt_pk_bf16_f32 v123, v126, v127
	s_waitcnt lgkmcnt(0)
	v_mfma_f32_32x32x16_bf16 v[64:79], v[2:5], v[128:131], v[64:79]
	v_mfma_f32_32x32x16_bf16 v[48:63], v[6:9], v[128:131], v[48:63]
	v_mfma_f32_32x32x16_bf16 v[64:79], v[12:15], v[136:139], v[64:79]
	v_mfma_f32_32x32x16_bf16 v[48:63], v[240:243], v[136:139], v[48:63]
